# noprio + IN epilogue row stats and shW prefetched to LDS by DMA at unit top (16 KiB static LDS)
# speedup vs baseline: 1.0089x; 1.0089x over previous
;     __host__ __device__ bool next(int i, Unit& u) const { if (i != 0 || S.c >= 2 * (S.nwg - base)) return false; S.unit_of(base + (S.c >> 1), u); u.hm = S.c & 1; return true; }
; template <class Epi, bool ALIGN_EPI, bool SP2, bool BF = false, bool HALFM = false, class Order = StaticOrder>
; __device__ __forceinline__ void gemm_phase(LAS unsigned char* lds, const int tid, const Gemm g, const Order& S, const Epi& E, const bool dry = false) {
;     ...
;     Unit cur, nxt; int ui = 0;
;     if (!S.next(0, cur)) return;
;     f32x4 acc[2][2][4][2];
; #pragma unroll
;     for (int a = 0; a < 2; ++a)
; #pragma unroll
;         for (int b = 0; b < 2; ++b)
; #pragma unroll
;             for (int m = 0; m < 4; ++m)
; #pragma unroll
;                 for (int n = 0; n < 2; ++n) acc[a][b][m][n] = (f32x4){0.f, 0.f, 0.f, 0.f};
;     ...
;     for (;;) {
;         const bool has_next = S.next(ui + 1, nxt);
;         const char* nA = has_next ? (const char*)g.A + (size_t)nxt.pm * tstep + (HALFM ? (size_t)nxt.hm * hstep : (size_t)0) : cA; const char* nB = has_next ? (const char*)g.Bt + (size_t)nxt.pn * tstep : cB;
.LBB0_560:
	s_ashr_i32 s21, s20, 31
	s_lshl_b64 s[8:9], s[20:21], 19
	s_add_u32 s22, s44, s8
	s_addc_u32 s23, s45, s9
	s_and_b64 s[8:9], s[0:1], exec
	s_cselect_b32 s3, s23, s39
	s_cselect_b32 s5, s22, s38
	s_ashr_i32 s19, s18, 31
	s_lshl_b64 s[8:9], s[18:19], 19
	s_add_u32 s24, s29, s8
	s_addc_u32 s25, s41, s9
	s_and_b64 s[8:9], s[0:1], exec
	s_cselect_b32 s8, s25, s37
	s_cselect_b32 s9, s24, s36
	s_add_u32 s11, s36, 0x100
	s_addc_u32 s19, s37, 0
	s_add_u32 s36, s38, 0x40080
	s_waitcnt vmcnt(0)
	v_mov_b32_e32 v58, 0
	s_addc_u32 s37, s39, 0
	s_mov_b32 s21, -2
	s_barrier
	v_readlane_b32 s100, v253, 0
	v_readlane_b32 s101, v253, 1
	v_readfirstlane_b32 vcc_hi, v212
	v_and_b32_e32 v132, 63, v212
	v_lshrrev_b32_e32 v133, 6, v212
	v_mul_u32_u24_e32 v133, 0x48000, v133
	v_lshlrev_b32_e32 v134, 4, v132
	v_add_u32_e32 v132, v134, v133
	s_lshl_b32 vcc_lo, s4, 10
	s_add_u32 vcc_lo, vcc_lo, 0x2880000
	v_add_u32_e32 v132, vcc_lo, v132
	s_lshl_b32 vcc_hi, vcc_hi, 5
	s_add_u32 m0, vcc_hi, 0x24000
	v_add_u32_e32 v133, 0x24000, v132
	global_load_lds_dwordx4 v132, s[100:101]
	s_add_u32 m0, vcc_hi, 0x24400
	s_nop 0
	global_load_lds_dwordx4 v133, s[100:101]
	s_cmp_lg_u32 vcc_hi, 0
	s_cbranch_scc1 .Lpf_noshw
	s_lshr_b32 vcc_lo, s4, 3
	s_cmpk_lt_u32 s4, 0x80
	s_cselect_b32 vcc_lo, vcc_lo, 16
	s_mul_i32 vcc_lo, vcc_lo, 0x3800
	s_lshl_b32 vcc_hi, s2, 10
	s_add_u32 vcc_lo, vcc_lo, vcc_hi
	s_add_u32 vcc_lo, vcc_lo, s96
	v_add_u32_e32 v134, vcc_lo, v134
	s_mov_b32 m0, 0x22400
	s_nop 0
	global_load_lds_dwordx4 v134, s[100:101]
.Lpf_noshw:
	v_mov_b32_e32 v59, v58
	v_mov_b32_e32 v60, v58
	v_mov_b32_e32 v61, v58
	v_mov_b32_e32 v62, v58
	v_mov_b32_e32 v63, v58
	v_mov_b32_e32 v64, v58
	v_mov_b32_e32 v65, v58
	v_mov_b32_e32 v74, v58
	v_mov_b32_e32 v75, v58
	v_mov_b32_e32 v76, v58
	v_mov_b32_e32 v77, v58
	v_mov_b32_e32 v78, v58
	v_mov_b32_e32 v79, v58
	v_mov_b32_e32 v80, v58
	v_mov_b32_e32 v81, v58
	v_mov_b32_e32 v82, v58
	v_mov_b32_e32 v83, v58
	v_mov_b32_e32 v84, v58
	v_mov_b32_e32 v85, v58
	v_mov_b32_e32 v86, v58
	v_mov_b32_e32 v87, v58
	v_mov_b32_e32 v88, v58
	v_mov_b32_e32 v89, v58
	v_mov_b32_e32 v90, v58
	v_mov_b32_e32 v91, v58
	v_mov_b32_e32 v92, v58
	v_mov_b32_e32 v93, v58
	v_mov_b32_e32 v94, v58
	v_mov_b32_e32 v95, v58
	v_mov_b32_e32 v96, v58
	v_mov_b32_e32 v97, v58
	v_mov_b32_e32 v2, v58
	v_mov_b32_e32 v3, v58
	v_mov_b32_e32 v4, v58
	v_mov_b32_e32 v5, v58
	v_mov_b32_e32 v6, v58
	v_mov_b32_e32 v7, v58
	v_mov_b32_e32 v8, v58
	v_mov_b32_e32 v9, v58
	v_mov_b32_e32 v10, v58
	v_mov_b32_e32 v11, v58
	v_mov_b32_e32 v12, v58
	v_mov_b32_e32 v13, v58
	v_mov_b32_e32 v14, v58
	v_mov_b32_e32 v15, v58
	v_mov_b32_e32 v16, v58
	v_mov_b32_e32 v17, v58
	v_mov_b32_e32 v18, v58
	v_mov_b32_e32 v19, v58
	v_mov_b32_e32 v20, v58
	v_mov_b32_e32 v21, v58
	v_mov_b32_e32 v22, v58
	v_mov_b32_e32 v23, v58
	v_mov_b32_e32 v24, v58
	v_mov_b32_e32 v25, v58
	v_mov_b32_e32 v26, v58
	v_mov_b32_e32 v27, v58
	v_mov_b32_e32 v28, v58
	v_mov_b32_e32 v29, v58
	v_mov_b32_e32 v30, v58
	v_mov_b32_e32 v31, v58
	v_mov_b32_e32 v32, v58
	v_mov_b32_e32 v33, v58
	v_mov_b32_e32 v98, v58
	v_mov_b32_e32 v99, v58
	v_mov_b32_e32 v100, v58
	v_mov_b32_e32 v101, v58
	v_mov_b32_e32 v102, v58
	v_mov_b32_e32 v103, v58
	v_mov_b32_e32 v104, v58
	v_mov_b32_e32 v105, v58
	v_mov_b32_e32 v106, v58
	v_mov_b32_e32 v107, v58
	v_mov_b32_e32 v108, v58
	v_mov_b32_e32 v109, v58
	v_mov_b32_e32 v110, v58
	v_mov_b32_e32 v111, v58
	v_mov_b32_e32 v112, v58
	v_mov_b32_e32 v113, v58
	v_mov_b32_e32 v114, v58
	v_mov_b32_e32 v115, v58
	v_mov_b32_e32 v116, v58
	v_mov_b32_e32 v117, v58
	v_mov_b32_e32 v118, v58
	v_mov_b32_e32 v119, v58
	v_mov_b32_e32 v120, v58
	v_mov_b32_e32 v121, v58
	v_mov_b32_e32 v122, v58
	v_mov_b32_e32 v123, v58
	v_mov_b32_e32 v124, v58
	v_mov_b32_e32 v125, v58
	v_mov_b32_e32 v126, v58
	v_mov_b32_e32 v127, v58
	v_mov_b32_e32 v128, v58
	v_mov_b32_e32 v129, v58
	v_mov_b32_e32 v34, v58
	v_mov_b32_e32 v35, v58
	v_mov_b32_e32 v36, v58
	v_mov_b32_e32 v37, v58
	v_mov_b32_e32 v38, v58
	v_mov_b32_e32 v39, v58
	v_mov_b32_e32 v40, v58
	v_mov_b32_e32 v41, v58
	v_mov_b32_e32 v42, v58
	v_mov_b32_e32 v43, v58
	v_mov_b32_e32 v44, v58
	v_mov_b32_e32 v45, v58
	v_mov_b32_e32 v54, v58
	v_mov_b32_e32 v55, v58
	v_mov_b32_e32 v56, v58
	v_mov_b32_e32 v57, v58
	v_mov_b32_e32 v46, v58
	v_mov_b32_e32 v47, v58
	v_mov_b32_e32 v48, v58
	v_mov_b32_e32 v49, v58
	v_mov_b32_e32 v50, v58
	v_mov_b32_e32 v51, v58
	v_mov_b32_e32 v52, v58
	v_mov_b32_e32 v53, v58
	v_mov_b32_e32 v66, v58
	v_mov_b32_e32 v67, v58
	v_mov_b32_e32 v68, v58
	v_mov_b32_e32 v69, v58
	v_mov_b32_e32 v70, v58
	v_mov_b32_e32 v71, v58
	v_mov_b32_e32 v72, v58
	v_mov_b32_e32 v73, v58

;     __device__ __forceinline__ void operator()(const f32x4 (&acc)[2][2][4][2], const pg8::Unit& u, int wr, int wc, int fr, int fq) const {
;     ...
;         const int rloc = wr * 64 + fr;
;         const unsigned rbase = (unsigned)u.pm * 256u + (unsigned)rloc;
;         float rs[2][4];
;         { float t[2][4][4];
; #pragma unroll
;           for (int ai = 0; ai < 2; ++ai)
; #pragma unroll
;             for (int m = 0; m < 4; ++m)
; #pragma unroll
;               for (int j = 0; j < 4; ++j) t[ai][m][j] = ldg_f1(ws, (unsigned)WS_ROWSQ + ((unsigned)(4 * fq + j) * (unsigned)MROWS + rbase + ai * 128 + m * 16) * 4u);
; #pragma unroll
;           for (int ai = 0; ai < 2; ++ai)
; #pragma unroll
;             for (int m = 0; m < 4; ++m) rs[ai][m] = __builtin_amdgcn_rsqf(red4((t[ai][m][0] + t[ai][m][1]) + (t[ai][m][2] + t[ai][m][3]), fq * 16 + fr) * (1.f / 1024.f) + EPS); }
;         const bool mapA = s >= 12 && s <= 21;
;         f32x4 bv[2][2];
; #pragma unroll
;         for (int bj = 0; bj < 2; ++bj)
; #pragma unroll
;             for (int n = 0; n < 2; ++n) bv[bj][n] = ldg_f4(ws, shw_off + (unsigned)(bb * NPAD + u.pn * 256 + 128 * bj + 32 * wc + 16 * n + 4 * fq) * 4u);
.LBB0_569:
	s_and_b64 s[8:9], s[14:15], exec
	s_cselect_b32 s37, 0, s43
	s_cselect_b32 s36, 0, s42
	s_lshl_b32 s19, s4, 8
	s_add_i32 s5, s19, s77
	v_add_u32_e32 v201, s5, v202
	v_lshlrev_b32_e32 v132, 12, v200
	v_lshl_add_u32 v132, v202, 2, v132
	s_lshl_b32 s5, s77, 2
	s_add_i32 s5, s5, 0x24000
	v_add_u32_e32 v132, s5, v132
	ds_read_b32 v133, v132 offset:0
	ds_read_b32 v134, v132 offset:1024
	ds_read_b32 v135, v132 offset:2048
	ds_read_b32 v136, v132 offset:3072
	ds_read_b32 v137, v132 offset:64
	ds_read_b32 v138, v132 offset:1088
	ds_read_b32 v139, v132 offset:2112
	ds_read_b32 v140, v132 offset:3136
	ds_read_b32 v141, v132 offset:128
	ds_read_b32 v142, v132 offset:1152
	ds_read_b32 v143, v132 offset:2176
	ds_read_b32 v144, v132 offset:3200
	ds_read_b32 v145, v132 offset:192
	ds_read_b32 v146, v132 offset:1216
	ds_read_b32 v147, v132 offset:2240
	ds_read_b32 v148, v132 offset:3264
	ds_read_b32 v149, v132 offset:512
	ds_read_b32 v150, v132 offset:1536
	ds_read_b32 v151, v132 offset:2560
	ds_read_b32 v152, v132 offset:3584
	ds_read_b32 v153, v132 offset:576
	ds_read_b32 v154, v132 offset:1600
	ds_read_b32 v155, v132 offset:2624
	ds_read_b32 v156, v132 offset:3648
	ds_read_b32 v157, v132 offset:640
	ds_read_b32 v158, v132 offset:1664
	ds_read_b32 v159, v132 offset:2688
	ds_read_b32 v160, v132 offset:3712
	ds_read_b32 v161, v132 offset:704
	s_lshl_b32 s2, s2, 10
	ds_read_b32 v162, v132 offset:1728
	s_add_i32 s2, s96, s2
	ds_read_b32 v163, v132 offset:2752
	v_lshlrev_b32_e32 v203, 4, v200
	ds_read_b32 v132, v132 offset:3776
	s_add_i32 s2, s3, s2
	s_waitcnt lgkmcnt(0)
	v_add_f32_e32 v133, v133, v134
	v_add_f32_e32 v134, v135, v136
	v_add_f32_e32 v133, v133, v134
	v_mov_b32_e32 v134, v133
	s_nop 1
	v_permlane16_swap_b32_e32 v133, v134
	v_add_f32_e32 v133, v133, v134
	v_mov_b32_e32 v134, v133
	s_nop 1
	v_permlane32_swap_b32_e32 v133, v134
	v_add_f32_e32 v133, v133, v134
	v_fmamk_f32 v133, v133, 0x3a800000, v229
	v_rsq_f32_e32 v176, v133
	v_add_f32_e32 v133, v137, v138
	v_add_f32_e32 v134, v139, v140
	v_add_f32_e32 v133, v133, v134
	v_mov_b32_e32 v134, v133
	s_nop 1
	v_permlane16_swap_b32_e32 v133, v134
	v_add_f32_e32 v133, v133, v134
	v_mov_b32_e32 v134, v133
	s_nop 1
	v_permlane32_swap_b32_e32 v133, v134
	v_add_f32_e32 v133, v133, v134
	v_fmamk_f32 v133, v133, 0x3a800000, v229
	v_rsq_f32_e32 v177, v133
	v_add_f32_e32 v133, v141, v142
	v_add_f32_e32 v134, v143, v144
	v_add_f32_e32 v133, v133, v134
	v_mov_b32_e32 v134, v133
	s_nop 1
	v_permlane16_swap_b32_e32 v133, v134
	v_add_f32_e32 v133, v133, v134
	v_mov_b32_e32 v134, v133
	s_nop 1
	v_permlane32_swap_b32_e32 v133, v134
	v_add_f32_e32 v133, v133, v134
	v_fmamk_f32 v133, v133, 0x3a800000, v229
	s_lshl_b32 s5, s76, 7
	s_add_i32 s5, s5, 0x22400
	v_add_u32_e32 v144, s5, v203
	v_rsq_f32_e32 v174, v133
	v_add_f32_e32 v134, v147, v148
	ds_read_b128 v[136:139], v144
	v_add_f32_e32 v133, v145, v146
	v_add_f32_e32 v133, v133, v134
	v_mov_b32_e32 v134, v133
	s_nop 1
	v_permlane16_swap_b32_e32 v133, v134
	v_add_f32_e32 v133, v133, v134
	v_mov_b32_e32 v134, v133
	s_nop 1
	v_permlane32_swap_b32_e32 v133, v134
	v_add_f32_e32 v133, v133, v134
	v_fmamk_f32 v133, v133, 0x3a800000, v229
	v_rsq_f32_e32 v175, v133
	v_add_f32_e32 v133, v149, v150
	v_add_f32_e32 v134, v151, v152
	v_add_f32_e32 v133, v133, v134
	v_mov_b32_e32 v134, v133
	s_nop 1
	v_permlane16_swap_b32_e32 v133, v134
	v_add_f32_e32 v133, v133, v134
	v_mov_b32_e32 v134, v133
	s_nop 1
	v_permlane32_swap_b32_e32 v133, v134
	v_add_f32_e32 v133, v133, v134
	v_fmamk_f32 v133, v133, 0x3a800000, v229
	v_rsq_f32_e32 v172, v133
	v_add_f32_e32 v133, v153, v154
	v_add_f32_e32 v134, v155, v156
	v_add_f32_e32 v133, v133, v134
	v_mov_b32_e32 v134, v133
	s_nop 1
	v_permlane16_swap_b32_e32 v133, v134
	v_add_f32_e32 v133, v133, v134
	v_mov_b32_e32 v134, v133
	s_nop 1
	v_permlane32_swap_b32_e32 v133, v134
	v_add_f32_e32 v133, v133, v134
	v_fmamk_f32 v133, v133, 0x3a800000, v229
	v_rsq_f32_e32 v173, v133
	v_add_f32_e32 v133, v157, v158
	v_add_f32_e32 v134, v159, v160
	v_add_f32_e32 v133, v133, v134
	v_mov_b32_e32 v134, v133
	s_nop 1
	v_permlane16_swap_b32_e32 v133, v134
	v_add_f32_e32 v133, v133, v134
	v_mov_b32_e32 v134, v133
	s_nop 1
	v_permlane32_swap_b32_e32 v133, v134
	v_add_f32_e32 v133, v133, v134
	v_fmamk_f32 v133, v133, 0x3a800000, v229
	v_rsq_f32_e32 v170, v133
	v_add_f32_e32 v133, v161, v162
	v_add_f32_e32 v132, v163, v132
	v_add_f32_e32 v132, v133, v132
	v_mov_b32_e32 v133, v132
	s_nop 1
	v_permlane16_swap_b32_e32 v132, v133
	v_add_f32_e32 v132, v132, v133
	v_mov_b32_e32 v133, v132
	s_nop 1
	v_permlane32_swap_b32_e32 v132, v133
	v_add_f32_e32 v132, v132, v133
	v_fmamk_f32 v132, v132, 0x3a800000, v229
	v_rsq_f32_e32 v171, v132
	ds_read_b128 v[132:135], v144 offset:64
	s_and_b32 s2, s19, 0x700
	ds_read_b128 v[140:143], v144 offset:512
	s_add_i32 s5, s2, 0x100
	ds_read_b128 v[144:147], v144 offset:576
	s_waitcnt lgkmcnt(0)
	s_and_b64 s[2:3], s[38:39], exec
	s_cselect_b32 s97, s5, 0
	s_sub_i32 s8, s11, 22
	s_mov_b64 s[2:3], -1
	s_cmp_gt_u32 s8, -11
	s_cbranch_scc0 .LBB0_592
	s_cmp_lt_u32 s78, 20
	s_cselect_b64 s[2:3], -1, 0
	v_readlane_b32 s56, v252, 28
	s_and_b64 s[42:43], s[2:3], exec
	v_readlane_b32 s60, v252, 32
	v_readlane_b32 s62, v252, 34
	v_readlane_b32 s61, v252, 33
	v_readlane_b32 s63, v252, 35
	s_cselect_b32 s9, s60, s62
	v_lshlrev_b32_e32 v186, 2, v200
	s_cselect_b32 s5, s61, s63
	s_add_u32 s42, s9, s16
	s_addc_u32 s43, s5, s17
	v_ashrrev_i32_e32 v187, 31, v186
	v_lshl_add_u64 v[148:149], v[186:187], 2, s[42:43]
	global_load_dwordx4 v[160:163], v[148:149], off
	global_load_dwordx4 v[156:159], v[148:149], off offset:64
	global_load_dwordx4 v[152:155], v[148:149], off offset:128
	s_nop 0
	global_load_dwordx4 v[148:151], v[148:149], off offset:192
	v_and_b32_e32 v178, -2, v202
	s_cmp_gt_u32 s78, 19
	v_add_u32_e32 v178, s77, v178
	s_mov_b64 s[42:43], -1
	v_readlane_b32 s57, v252, 29
	v_readlane_b32 s58, v252, 30
	v_readlane_b32 s59, v252, 31
	v_readlane_b32 s64, v252, 36
	v_readlane_b32 s65, v252, 37
	v_readlane_b32 s66, v252, 38
	v_readlane_b32 s67, v252, 39
	v_readlane_b32 s68, v252, 40
	v_readlane_b32 s69, v252, 41
	v_readlane_b32 s70, v252, 42
	v_readlane_b32 s71, v252, 43
	s_cbranch_scc0 .LBB0_572
	s_lshl_b32 s5, s21, 1
	s_add_i32 s5, s11, s5
	s_mulk_i32 s5, 0x900
	s_add_i32 s5, s5, s97
	s_add_i32 s5, s5, 0xffff4c00
	v_add_u32_e32 v179, s5, v178
	v_mov_b32_e32 v180, 0x10380000
	v_lshl_add_u32 v187, v179, 7, v180
	s_mov_b64 s[42:43], 0

; __global__ void __launch_bounds__(NTHREADS, 2) mega(Args a) {
	.amdhsa_kernel _Z4mega4Args
		.amdhsa_group_segment_fixed_size 16384
		.amdhsa_private_segment_fixed_size 0
		.amdhsa_kernarg_size 416
		.amdhsa_user_sgpr_count 2
		.amdhsa_user_sgpr_dispatch_ptr 0
		.amdhsa_user_sgpr_queue_ptr 0
		.amdhsa_user_sgpr_kernarg_segment_ptr 1
		.amdhsa_user_sgpr_dispatch_id 0
		.amdhsa_user_sgpr_kernarg_preload_length 0
		.amdhsa_user_sgpr_kernarg_preload_offset 0
		.amdhsa_user_sgpr_private_segment_size 0
		.amdhsa_uses_dynamic_stack 0
		.amdhsa_enable_private_segment 0
		.amdhsa_system_sgpr_workgroup_id_x 1
		.amdhsa_system_sgpr_workgroup_id_y 0
		.amdhsa_system_sgpr_workgroup_id_z 0
		.amdhsa_system_sgpr_workgroup_info 0
		.amdhsa_system_vgpr_workitem_id 0
		.amdhsa_next_free_vgpr 256
		.amdhsa_next_free_sgpr 102
		.amdhsa_accum_offset 256
		.amdhsa_reserve_vcc 1
		.amdhsa_float_round_mode_32 0
		.amdhsa_float_round_mode_16_64 0
		.amdhsa_float_denorm_mode_32 3
		.amdhsa_float_denorm_mode_16_64 3
		.amdhsa_dx10_clamp 1
		.amdhsa_ieee_mode 1
		.amdhsa_fp16_overflow 0
		.amdhsa_tg_split 0
		.amdhsa_exception_fp_ieee_invalid_op 0
		.amdhsa_exception_fp_denorm_src 0
		.amdhsa_exception_fp_ieee_div_zero 0
		.amdhsa_exception_fp_ieee_overflow 0
		.amdhsa_exception_fp_ieee_underflow 0
		.amdhsa_exception_fp_ieee_inexact 0
		.amdhsa_exception_int_div_zero 0
	.end_amdhsa_kernel

; __global__ void __launch_bounds__(NTHREADS, 2) mega(Args a) {
amdhsa.kernels:
  - .agpr_count:     0
    .args:
      - .offset:         0
        .size:           160
        .value_kind:     by_value
      - .offset:         160
        .size:           4
        .value_kind:     hidden_block_count_x
      - .offset:         164
        .size:           4
        .value_kind:     hidden_block_count_y
      - .offset:         168
        .size:           4
        .value_kind:     hidden_block_count_z
      - .offset:         172
        .size:           2
        .value_kind:     hidden_group_size_x
      - .offset:         174
        .size:           2
        .value_kind:     hidden_group_size_y
      - .offset:         176
        .size:           2
        .value_kind:     hidden_group_size_z
      - .offset:         178
        .size:           2
        .value_kind:     hidden_remainder_x
      - .offset:         180
        .size:           2
        .value_kind:     hidden_remainder_y
      - .offset:         182
        .size:           2
        .value_kind:     hidden_remainder_z
      - .offset:         200
        .size:           8
        .value_kind:     hidden_global_offset_x
      - .offset:         208
        .size:           8
        .value_kind:     hidden_global_offset_y
      - .offset:         216
        .size:           8
        .value_kind:     hidden_global_offset_z
      - .offset:         224
        .size:           2
        .value_kind:     hidden_grid_dims
      - .offset:         280
        .size:           4
        .value_kind:     hidden_dynamic_lds_size
    .group_segment_fixed_size: 16384
    .kernarg_segment_align: 8
    .kernarg_segment_size: 416
    .language:       OpenCL C
    .language_version:
      - 2
      - 0
    .max_flat_workgroup_size: 512
    .name:           _Z4mega4Args
    .private_segment_fixed_size: 0
    .sgpr_count:     108
    .sgpr_spill_count: 295
    .symbol:         _Z4mega4Args.kd
    .uniform_work_group_size: 1
    .uses_dynamic_stack: false
    .vgpr_count:     256
    .vgpr_spill_count: 0
    .wavefront_size: 64
